# static s_setprio 1 for waves 4-7 extended to the norm / token phases (all phases except the D GEMMs and attention)
# baseline (speedup 1.0000x reference)
.LBB0_158:
	s_or_b64 exec, exec, s[2:3]
.LBB0_159:
	v_readfirstlane_b32 s99, v0
	s_cmp_lt_u32 s99, 0x100
	s_cbranch_scc1 .Lprio_skip1
	s_setprio 1
.Lprio_skip1:
	s_cmp_gt_i32 s18, 1
	s_cselect_b64 s[4:5], -1, 0
	s_cmp_lt_i32 s19, 2
	s_cselect_b64 s[2:3], -1, 0
	s_or_b64 s[2:3], s[4:5], s[2:3]
	s_and_b64 vcc, exec, s[2:3]
	s_cbranch_vccnz .LBB0_224
	s_andn2_b64 vcc, exec, s[8:9]
	s_cbranch_vccnz .LBB0_162
	s_cbranch_execz .LBB0_163
	s_branch .LBB0_216

.LBB0_436:
	s_setprio 0
	s_cmp_gt_i32 s18, 4
	s_cselect_b64 s[8:9], -1, 0
	s_cmp_lt_i32 s19, 5
	s_cselect_b64 s[2:3], -1, 0
	s_or_b64 s[2:3], s[8:9], s[2:3]
	s_and_b64 vcc, exec, s[2:3]
	s_cbranch_vccnz .LBB0_717
	s_andn2_b64 vcc, exec, s[20:21]
	s_cbranch_vccnz .LBB0_439
	s_cbranch_execz .LBB0_440
	s_branch .LBB0_493

.LBB0_1679:
	s_setprio 0
	s_cmp_gt_i32 s18, 13
	s_cselect_b64 s[8:9], -1, 0
	s_cmp_lt_i32 s19, 14
	s_cselect_b64 s[2:3], -1, 0
	s_or_b64 s[2:3], s[8:9], s[2:3]
	s_and_b64 vcc, exec, s[2:3]
	s_cbranch_vccnz .LBB0_1960
	s_andn2_b64 vcc, exec, s[20:21]
	s_cbranch_vccnz .LBB0_1682
	s_cbranch_execz .LBB0_1683
	s_branch .LBB0_1736
